# GEMM k-loops: counted lgkmcnt ladder before every MFMA cluster; PEER pass-1 dot products interleaved in row pairs
# speedup vs baseline: 1.0474x; 1.0083x over previous
.Lpu_tokA_in:
	v_lshlrev_b32_e32 v108, 16, v20
	v_and_b32_e32 v109, 0xffff0000, v20
	v_lshlrev_b32_e32 v110, 16, v21
	v_and_b32_e32 v111, 0xffff0000, v21
	v_lshlrev_b32_e32 v112, 16, v22
	v_and_b32_e32 v113, 0xffff0000, v22
	v_lshlrev_b32_e32 v114, 16, v23
	v_and_b32_e32 v115, 0xffff0000, v23
	v_lshlrev_b32_e32 v238, 16, v24
	v_and_b32_e32 v239, 0xffff0000, v24
	v_lshlrev_b32_e32 v240, 16, v25
	v_and_b32_e32 v241, 0xffff0000, v25
	v_lshlrev_b32_e32 v242, 16, v26
	v_and_b32_e32 v243, 0xffff0000, v26
	v_lshlrev_b32_e32 v244, 16, v27
	v_and_b32_e32 v245, 0xffff0000, v27
	ds_bpermute_b32 v124, v4, v10
	ds_bpermute_b32 v125, v12, v10
	ds_bpermute_b32 v126, v13, v10
	ds_bpermute_b32 v127, v14, v10
	ds_bpermute_b32 v128, v15, v10
	ds_bpermute_b32 v129, v16, v10
	ds_bpermute_b32 v130, v17, v10
	ds_bpermute_b32 v131, v18, v10
	s_waitcnt lgkmcnt(0)
	v_lshl_add_u32 v124, v124, 7, v1
	v_lshl_add_u32 v125, v125, 7, v1
	v_lshl_add_u32 v126, v126, 7, v1
	v_lshl_add_u32 v127, v127, 7, v1
	v_lshl_add_u32 v128, v128, 7, v1
	v_lshl_add_u32 v129, v129, 7, v1
	v_lshl_add_u32 v130, v130, 7, v1
	v_lshl_add_u32 v131, v131, 7, v1
	global_load_dwordx4 v[198:201], v124, s[44:45]
	global_load_dwordx4 v[202:205], v125, s[44:45]
	global_load_dwordx4 v[206:209], v126, s[44:45]
	global_load_dwordx4 v[210:213], v127, s[44:45]
	global_load_dwordx4 v[214:217], v128, s[44:45]
	global_load_dwordx4 v[218:221], v129, s[44:45]
	global_load_dwordx4 v[222:225], v130, s[44:45]
	global_load_dwordx4 v[226:229], v131, s[44:45]
	ds_bpermute_b32 v124, v4, v11
	ds_bpermute_b32 v125, v12, v11
	ds_bpermute_b32 v126, v13, v11
	ds_bpermute_b32 v127, v14, v11
	ds_bpermute_b32 v128, v15, v11
	ds_bpermute_b32 v129, v16, v11
	ds_bpermute_b32 v130, v17, v11
	ds_bpermute_b32 v131, v18, v11
	s_waitcnt lgkmcnt(0)
	v_lshl_add_u32 v124, v124, 7, v1
	v_lshl_add_u32 v125, v125, 7, v1
	v_lshl_add_u32 v126, v126, 7, v1
	v_lshl_add_u32 v127, v127, 7, v1
	v_lshl_add_u32 v128, v128, 7, v1
	v_lshl_add_u32 v129, v129, 7, v1
	v_lshl_add_u32 v130, v130, 7, v1
	v_lshl_add_u32 v131, v131, 7, v1
	global_load_dwordx4 v[230:233], v124, s[44:45]
	global_load_dwordx4 v[234:237], v125, s[44:45]
	global_load_dwordx4 v[138:141], v126, s[44:45]
	global_load_dwordx4 v[142:145], v127, s[44:45]
	global_load_dwordx4 v[146:149], v128, s[44:45]
	global_load_dwordx4 v[150:153], v129, s[44:45]
	global_load_dwordx4 v[154:157], v130, s[44:45]
	global_load_dwordx4 v[158:161], v131, s[44:45]
	s_lshl_b32 s1, s39, 1
	s_add_i32 s1, s1, s38
	s_min_u32 s1, s1, 0xffff
	s_lshl_b32 s0, s1, 9
	v_add_u32_e32 v0, s0, v6
	global_load_dword v10, v0, s[42:43]
	global_load_dword v11, v0, s[42:43] offset:256
	s_lshl_b32 s0, s1, 11
	v_add_u32_e32 v0, s0, v2
	global_load_dwordx4 v[20:23], v0, s[48:49]
	global_load_dwordx4 v[24:27], v0, s[48:49] offset:16
	v_cvt_pk_f32_fp8_e32 v[118:119], v44
	v_cvt_pk_f32_fp8_e32 v[122:123], v48
	v_cvt_pk_f32_fp8_sdwa v[120:121], v44 src0_sel:WORD_1
	v_cvt_pk_f32_fp8_sdwa v[246:247], v48 src0_sel:WORD_1
	v_pk_mul_f32 v[8:9], v[118:119], v[28:29]
	v_pk_mul_f32 v[116:117], v[122:123], v[28:29]
	v_cvt_pk_f32_fp8_e32 v[118:119], v45
	v_cvt_pk_f32_fp8_e32 v[122:123], v49
	v_pk_fma_f32 v[8:9], v[120:121], v[30:31], v[8:9]
	v_pk_fma_f32 v[116:117], v[246:247], v[30:31], v[116:117]
	v_cvt_pk_f32_fp8_sdwa v[120:121], v45 src0_sel:WORD_1
	v_cvt_pk_f32_fp8_sdwa v[246:247], v49 src0_sel:WORD_1
	v_pk_fma_f32 v[8:9], v[118:119], v[32:33], v[8:9]
	v_pk_fma_f32 v[116:117], v[122:123], v[32:33], v[116:117]
	v_cvt_pk_f32_fp8_e32 v[118:119], v46
	v_cvt_pk_f32_fp8_e32 v[122:123], v50
	v_pk_fma_f32 v[8:9], v[120:121], v[34:35], v[8:9]
	v_pk_fma_f32 v[116:117], v[246:247], v[34:35], v[116:117]
	v_cvt_pk_f32_fp8_sdwa v[120:121], v46 src0_sel:WORD_1
	v_cvt_pk_f32_fp8_sdwa v[246:247], v50 src0_sel:WORD_1
	v_pk_fma_f32 v[8:9], v[118:119], v[36:37], v[8:9]
	v_pk_fma_f32 v[116:117], v[122:123], v[36:37], v[116:117]
	v_cvt_pk_f32_fp8_e32 v[118:119], v47
	v_cvt_pk_f32_fp8_e32 v[122:123], v51
	v_pk_fma_f32 v[8:9], v[120:121], v[38:39], v[8:9]
	v_pk_fma_f32 v[116:117], v[246:247], v[38:39], v[116:117]
	v_cvt_pk_f32_fp8_sdwa v[120:121], v47 src0_sel:WORD_1
	v_cvt_pk_f32_fp8_sdwa v[246:247], v51 src0_sel:WORD_1
	v_pk_fma_f32 v[8:9], v[118:119], v[40:41], v[8:9]
	v_pk_fma_f32 v[116:117], v[122:123], v[40:41], v[116:117]
	v_pk_fma_f32 v[8:9], v[120:121], v[42:43], v[8:9]
	v_pk_fma_f32 v[116:117], v[246:247], v[42:43], v[116:117]
	v_add_f32_e32 v124, v8, v9
	v_add_f32_e32 v125, v116, v117
	v_cvt_pk_f32_fp8_e32 v[118:119], v52
	v_cvt_pk_f32_fp8_e32 v[122:123], v56
	v_cvt_pk_f32_fp8_sdwa v[120:121], v52 src0_sel:WORD_1
	v_cvt_pk_f32_fp8_sdwa v[246:247], v56 src0_sel:WORD_1
	v_pk_mul_f32 v[8:9], v[118:119], v[28:29]
	v_pk_mul_f32 v[116:117], v[122:123], v[28:29]
	v_cvt_pk_f32_fp8_e32 v[118:119], v53
	v_cvt_pk_f32_fp8_e32 v[122:123], v57
	v_pk_fma_f32 v[8:9], v[120:121], v[30:31], v[8:9]
	v_pk_fma_f32 v[116:117], v[246:247], v[30:31], v[116:117]
	v_cvt_pk_f32_fp8_sdwa v[120:121], v53 src0_sel:WORD_1
	v_cvt_pk_f32_fp8_sdwa v[246:247], v57 src0_sel:WORD_1
	v_pk_fma_f32 v[8:9], v[118:119], v[32:33], v[8:9]
	v_pk_fma_f32 v[116:117], v[122:123], v[32:33], v[116:117]
	v_cvt_pk_f32_fp8_e32 v[118:119], v54
	v_cvt_pk_f32_fp8_e32 v[122:123], v58
	v_pk_fma_f32 v[8:9], v[120:121], v[34:35], v[8:9]
	v_pk_fma_f32 v[116:117], v[246:247], v[34:35], v[116:117]
	v_cvt_pk_f32_fp8_sdwa v[120:121], v54 src0_sel:WORD_1
	v_cvt_pk_f32_fp8_sdwa v[246:247], v58 src0_sel:WORD_1
	v_pk_fma_f32 v[8:9], v[118:119], v[36:37], v[8:9]
	v_pk_fma_f32 v[116:117], v[122:123], v[36:37], v[116:117]
	v_cvt_pk_f32_fp8_e32 v[118:119], v55
	v_cvt_pk_f32_fp8_e32 v[122:123], v59
	v_pk_fma_f32 v[8:9], v[120:121], v[38:39], v[8:9]
	v_pk_fma_f32 v[116:117], v[246:247], v[38:39], v[116:117]
	v_cvt_pk_f32_fp8_sdwa v[120:121], v55 src0_sel:WORD_1
	v_cvt_pk_f32_fp8_sdwa v[246:247], v59 src0_sel:WORD_1
	v_pk_fma_f32 v[8:9], v[118:119], v[40:41], v[8:9]
	v_pk_fma_f32 v[116:117], v[122:123], v[40:41], v[116:117]
	v_pk_fma_f32 v[8:9], v[120:121], v[42:43], v[8:9]
	v_pk_fma_f32 v[116:117], v[246:247], v[42:43], v[116:117]
	v_add_f32_e32 v126, v8, v9
	v_add_f32_e32 v127, v116, v117
	v_cvt_pk_f32_fp8_e32 v[118:119], v60
	v_cvt_pk_f32_fp8_e32 v[122:123], v64
	v_cvt_pk_f32_fp8_sdwa v[120:121], v60 src0_sel:WORD_1
	v_cvt_pk_f32_fp8_sdwa v[246:247], v64 src0_sel:WORD_1
	v_pk_mul_f32 v[8:9], v[118:119], v[28:29]
	v_pk_mul_f32 v[116:117], v[122:123], v[28:29]
	v_cvt_pk_f32_fp8_e32 v[118:119], v61
	v_cvt_pk_f32_fp8_e32 v[122:123], v65
	v_pk_fma_f32 v[8:9], v[120:121], v[30:31], v[8:9]
	v_pk_fma_f32 v[116:117], v[246:247], v[30:31], v[116:117]
	v_cvt_pk_f32_fp8_sdwa v[120:121], v61 src0_sel:WORD_1
	v_cvt_pk_f32_fp8_sdwa v[246:247], v65 src0_sel:WORD_1
	v_pk_fma_f32 v[8:9], v[118:119], v[32:33], v[8:9]
	v_pk_fma_f32 v[116:117], v[122:123], v[32:33], v[116:117]
	v_cvt_pk_f32_fp8_e32 v[118:119], v62
	v_cvt_pk_f32_fp8_e32 v[122:123], v66
	v_pk_fma_f32 v[8:9], v[120:121], v[34:35], v[8:9]
	v_pk_fma_f32 v[116:117], v[246:247], v[34:35], v[116:117]
	v_cvt_pk_f32_fp8_sdwa v[120:121], v62 src0_sel:WORD_1
	v_cvt_pk_f32_fp8_sdwa v[246:247], v66 src0_sel:WORD_1
	v_pk_fma_f32 v[8:9], v[118:119], v[36:37], v[8:9]
	v_pk_fma_f32 v[116:117], v[122:123], v[36:37], v[116:117]
	v_cvt_pk_f32_fp8_e32 v[118:119], v63
	v_cvt_pk_f32_fp8_e32 v[122:123], v67
	v_pk_fma_f32 v[8:9], v[120:121], v[38:39], v[8:9]
	v_pk_fma_f32 v[116:117], v[246:247], v[38:39], v[116:117]
	v_cvt_pk_f32_fp8_sdwa v[120:121], v63 src0_sel:WORD_1
	v_cvt_pk_f32_fp8_sdwa v[246:247], v67 src0_sel:WORD_1
	v_pk_fma_f32 v[8:9], v[118:119], v[40:41], v[8:9]
	v_pk_fma_f32 v[116:117], v[122:123], v[40:41], v[116:117]
	v_pk_fma_f32 v[8:9], v[120:121], v[42:43], v[8:9]
	v_pk_fma_f32 v[116:117], v[246:247], v[42:43], v[116:117]
	v_add_f32_e32 v128, v8, v9
	v_add_f32_e32 v129, v116, v117
	v_cvt_pk_f32_fp8_e32 v[118:119], v68
	v_cvt_pk_f32_fp8_e32 v[122:123], v72
	v_cvt_pk_f32_fp8_sdwa v[120:121], v68 src0_sel:WORD_1
	v_cvt_pk_f32_fp8_sdwa v[246:247], v72 src0_sel:WORD_1
	v_pk_mul_f32 v[8:9], v[118:119], v[28:29]
	v_pk_mul_f32 v[116:117], v[122:123], v[28:29]
	v_cvt_pk_f32_fp8_e32 v[118:119], v69
	v_cvt_pk_f32_fp8_e32 v[122:123], v73
	v_pk_fma_f32 v[8:9], v[120:121], v[30:31], v[8:9]
	v_pk_fma_f32 v[116:117], v[246:247], v[30:31], v[116:117]
	v_cvt_pk_f32_fp8_sdwa v[120:121], v69 src0_sel:WORD_1
	v_cvt_pk_f32_fp8_sdwa v[246:247], v73 src0_sel:WORD_1
	v_pk_fma_f32 v[8:9], v[118:119], v[32:33], v[8:9]
	v_pk_fma_f32 v[116:117], v[122:123], v[32:33], v[116:117]
	v_cvt_pk_f32_fp8_e32 v[118:119], v70
	v_cvt_pk_f32_fp8_e32 v[122:123], v74
	v_pk_fma_f32 v[8:9], v[120:121], v[34:35], v[8:9]
	v_pk_fma_f32 v[116:117], v[246:247], v[34:35], v[116:117]
	v_cvt_pk_f32_fp8_sdwa v[120:121], v70 src0_sel:WORD_1
	v_cvt_pk_f32_fp8_sdwa v[246:247], v74 src0_sel:WORD_1
	v_pk_fma_f32 v[8:9], v[118:119], v[36:37], v[8:9]
	v_pk_fma_f32 v[116:117], v[122:123], v[36:37], v[116:117]
	v_cvt_pk_f32_fp8_e32 v[118:119], v71
	v_cvt_pk_f32_fp8_e32 v[122:123], v75
	v_pk_fma_f32 v[8:9], v[120:121], v[38:39], v[8:9]
	v_pk_fma_f32 v[116:117], v[246:247], v[38:39], v[116:117]
	v_cvt_pk_f32_fp8_sdwa v[120:121], v71 src0_sel:WORD_1
	v_cvt_pk_f32_fp8_sdwa v[246:247], v75 src0_sel:WORD_1
	v_pk_fma_f32 v[8:9], v[118:119], v[40:41], v[8:9]
	v_pk_fma_f32 v[116:117], v[122:123], v[40:41], v[116:117]
	v_pk_fma_f32 v[8:9], v[120:121], v[42:43], v[8:9]
	v_pk_fma_f32 v[116:117], v[246:247], v[42:43], v[116:117]
	v_add_f32_e32 v130, v8, v9
	v_add_f32_e32 v131, v116, v117
	v_cndmask_b32_e32 v116, v124, v128, vcc
	v_cndmask_b32_e32 v117, v128, v124, vcc
	v_cndmask_b32_e32 v118, v125, v129, vcc
	v_cndmask_b32_e32 v119, v129, v125, vcc
	v_cndmask_b32_e32 v120, v126, v130, vcc
	v_cndmask_b32_e32 v121, v130, v126, vcc
	v_cndmask_b32_e32 v122, v127, v131, vcc
	v_cndmask_b32_e32 v123, v131, v127, vcc
	v_add_f32_dpp v124, v117, v116 row_half_mirror row_mask:0xf bank_mask:0xf
	v_add_f32_dpp v125, v119, v118 row_half_mirror row_mask:0xf bank_mask:0xf
	v_add_f32_dpp v126, v121, v120 row_half_mirror row_mask:0xf bank_mask:0xf
	v_add_f32_dpp v127, v123, v122 row_half_mirror row_mask:0xf bank_mask:0xf
	v_cndmask_b32_e64 v116, v124, v126, s[34:35]
	v_cndmask_b32_e64 v117, v126, v124, s[34:35]
	v_cndmask_b32_e64 v118, v125, v127, s[34:35]
	v_cndmask_b32_e64 v119, v127, v125, s[34:35]
	s_nop 0
	v_add_f32_dpp v124, v117, v116 quad_perm:[2,3,0,1] row_mask:0xf bank_mask:0xf
	v_add_f32_dpp v125, v119, v118 quad_perm:[2,3,0,1] row_mask:0xf bank_mask:0xf
	v_cndmask_b32_e64 v116, v124, v125, s[30:31]
	v_cndmask_b32_e64 v117, v125, v124, s[30:31]
	s_nop 1
	v_add_f32_dpp v5, v117, v116 quad_perm:[1,0,3,2] row_mask:0xf bank_mask:0xf
	v_cvt_pk_f32_fp8_e32 v[118:119], v76
	v_cvt_pk_f32_fp8_e32 v[122:123], v80
	v_cvt_pk_f32_fp8_sdwa v[120:121], v76 src0_sel:WORD_1
	v_cvt_pk_f32_fp8_sdwa v[246:247], v80 src0_sel:WORD_1
	v_pk_mul_f32 v[8:9], v[118:119], v[28:29]
	v_pk_mul_f32 v[116:117], v[122:123], v[28:29]
	v_cvt_pk_f32_fp8_e32 v[118:119], v77
	v_cvt_pk_f32_fp8_e32 v[122:123], v81
	v_pk_fma_f32 v[8:9], v[120:121], v[30:31], v[8:9]
	v_pk_fma_f32 v[116:117], v[246:247], v[30:31], v[116:117]
	v_cvt_pk_f32_fp8_sdwa v[120:121], v77 src0_sel:WORD_1
	v_cvt_pk_f32_fp8_sdwa v[246:247], v81 src0_sel:WORD_1
	v_pk_fma_f32 v[8:9], v[118:119], v[32:33], v[8:9]
	v_pk_fma_f32 v[116:117], v[122:123], v[32:33], v[116:117]
	v_cvt_pk_f32_fp8_e32 v[118:119], v78
	v_cvt_pk_f32_fp8_e32 v[122:123], v82
	v_pk_fma_f32 v[8:9], v[120:121], v[34:35], v[8:9]
	v_pk_fma_f32 v[116:117], v[246:247], v[34:35], v[116:117]
	v_cvt_pk_f32_fp8_sdwa v[120:121], v78 src0_sel:WORD_1
	v_cvt_pk_f32_fp8_sdwa v[246:247], v82 src0_sel:WORD_1
	v_pk_fma_f32 v[8:9], v[118:119], v[36:37], v[8:9]
	v_pk_fma_f32 v[116:117], v[122:123], v[36:37], v[116:117]
	v_cvt_pk_f32_fp8_e32 v[118:119], v79
	v_cvt_pk_f32_fp8_e32 v[122:123], v83
	v_pk_fma_f32 v[8:9], v[120:121], v[38:39], v[8:9]
	v_pk_fma_f32 v[116:117], v[246:247], v[38:39], v[116:117]
	v_cvt_pk_f32_fp8_sdwa v[120:121], v79 src0_sel:WORD_1
	v_cvt_pk_f32_fp8_sdwa v[246:247], v83 src0_sel:WORD_1
	v_pk_fma_f32 v[8:9], v[118:119], v[40:41], v[8:9]
	v_pk_fma_f32 v[116:117], v[122:123], v[40:41], v[116:117]
	v_pk_fma_f32 v[8:9], v[120:121], v[42:43], v[8:9]
	v_pk_fma_f32 v[116:117], v[246:247], v[42:43], v[116:117]
	v_add_f32_e32 v124, v8, v9
	v_add_f32_e32 v125, v116, v117
	v_cvt_pk_f32_fp8_e32 v[118:119], v84
	v_cvt_pk_f32_fp8_e32 v[122:123], v88
	v_cvt_pk_f32_fp8_sdwa v[120:121], v84 src0_sel:WORD_1
	v_cvt_pk_f32_fp8_sdwa v[246:247], v88 src0_sel:WORD_1
	v_pk_mul_f32 v[8:9], v[118:119], v[28:29]
	v_pk_mul_f32 v[116:117], v[122:123], v[28:29]
	v_cvt_pk_f32_fp8_e32 v[118:119], v85
	v_cvt_pk_f32_fp8_e32 v[122:123], v89
	v_pk_fma_f32 v[8:9], v[120:121], v[30:31], v[8:9]
	v_pk_fma_f32 v[116:117], v[246:247], v[30:31], v[116:117]
	v_cvt_pk_f32_fp8_sdwa v[120:121], v85 src0_sel:WORD_1
	v_cvt_pk_f32_fp8_sdwa v[246:247], v89 src0_sel:WORD_1
	v_pk_fma_f32 v[8:9], v[118:119], v[32:33], v[8:9]
	v_pk_fma_f32 v[116:117], v[122:123], v[32:33], v[116:117]
	v_cvt_pk_f32_fp8_e32 v[118:119], v86
	v_cvt_pk_f32_fp8_e32 v[122:123], v90
	v_pk_fma_f32 v[8:9], v[120:121], v[34:35], v[8:9]
	v_pk_fma_f32 v[116:117], v[246:247], v[34:35], v[116:117]
	v_cvt_pk_f32_fp8_sdwa v[120:121], v86 src0_sel:WORD_1
	v_cvt_pk_f32_fp8_sdwa v[246:247], v90 src0_sel:WORD_1
	v_pk_fma_f32 v[8:9], v[118:119], v[36:37], v[8:9]
	v_pk_fma_f32 v[116:117], v[122:123], v[36:37], v[116:117]
	v_cvt_pk_f32_fp8_e32 v[118:119], v87
	v_cvt_pk_f32_fp8_e32 v[122:123], v91
	v_pk_fma_f32 v[8:9], v[120:121], v[38:39], v[8:9]
	v_pk_fma_f32 v[116:117], v[246:247], v[38:39], v[116:117]
	v_cvt_pk_f32_fp8_sdwa v[120:121], v87 src0_sel:WORD_1
	v_cvt_pk_f32_fp8_sdwa v[246:247], v91 src0_sel:WORD_1
	v_pk_fma_f32 v[8:9], v[118:119], v[40:41], v[8:9]
	v_pk_fma_f32 v[116:117], v[122:123], v[40:41], v[116:117]
	v_pk_fma_f32 v[8:9], v[120:121], v[42:43], v[8:9]
	v_pk_fma_f32 v[116:117], v[246:247], v[42:43], v[116:117]
	v_add_f32_e32 v126, v8, v9
	v_add_f32_e32 v127, v116, v117
	v_cvt_pk_f32_fp8_e32 v[118:119], v92
	v_cvt_pk_f32_fp8_e32 v[122:123], v96
	v_cvt_pk_f32_fp8_sdwa v[120:121], v92 src0_sel:WORD_1
	v_cvt_pk_f32_fp8_sdwa v[246:247], v96 src0_sel:WORD_1
	v_pk_mul_f32 v[8:9], v[118:119], v[28:29]
	v_pk_mul_f32 v[116:117], v[122:123], v[28:29]
	v_cvt_pk_f32_fp8_e32 v[118:119], v93
	v_cvt_pk_f32_fp8_e32 v[122:123], v97
	v_pk_fma_f32 v[8:9], v[120:121], v[30:31], v[8:9]
	v_pk_fma_f32 v[116:117], v[246:247], v[30:31], v[116:117]
	v_cvt_pk_f32_fp8_sdwa v[120:121], v93 src0_sel:WORD_1
	v_cvt_pk_f32_fp8_sdwa v[246:247], v97 src0_sel:WORD_1
	v_pk_fma_f32 v[8:9], v[118:119], v[32:33], v[8:9]
	v_pk_fma_f32 v[116:117], v[122:123], v[32:33], v[116:117]
	v_cvt_pk_f32_fp8_e32 v[118:119], v94
	v_cvt_pk_f32_fp8_e32 v[122:123], v98
	v_pk_fma_f32 v[8:9], v[120:121], v[34:35], v[8:9]
	v_pk_fma_f32 v[116:117], v[246:247], v[34:35], v[116:117]
	v_cvt_pk_f32_fp8_sdwa v[120:121], v94 src0_sel:WORD_1
	v_cvt_pk_f32_fp8_sdwa v[246:247], v98 src0_sel:WORD_1
	v_pk_fma_f32 v[8:9], v[118:119], v[36:37], v[8:9]
	v_pk_fma_f32 v[116:117], v[122:123], v[36:37], v[116:117]
	v_cvt_pk_f32_fp8_e32 v[118:119], v95
	v_cvt_pk_f32_fp8_e32 v[122:123], v99
	v_pk_fma_f32 v[8:9], v[120:121], v[38:39], v[8:9]
	v_pk_fma_f32 v[116:117], v[246:247], v[38:39], v[116:117]
	v_cvt_pk_f32_fp8_sdwa v[120:121], v95 src0_sel:WORD_1
	v_cvt_pk_f32_fp8_sdwa v[246:247], v99 src0_sel:WORD_1
	v_pk_fma_f32 v[8:9], v[118:119], v[40:41], v[8:9]
	v_pk_fma_f32 v[116:117], v[122:123], v[40:41], v[116:117]
	v_pk_fma_f32 v[8:9], v[120:121], v[42:43], v[8:9]
	v_pk_fma_f32 v[116:117], v[246:247], v[42:43], v[116:117]
	v_add_f32_e32 v128, v8, v9
	v_add_f32_e32 v129, v116, v117
	v_cvt_pk_f32_fp8_e32 v[118:119], v100
	v_cvt_pk_f32_fp8_e32 v[122:123], v104
	v_cvt_pk_f32_fp8_sdwa v[120:121], v100 src0_sel:WORD_1
	v_cvt_pk_f32_fp8_sdwa v[246:247], v104 src0_sel:WORD_1
	v_pk_mul_f32 v[8:9], v[118:119], v[28:29]
	v_pk_mul_f32 v[116:117], v[122:123], v[28:29]
	v_cvt_pk_f32_fp8_e32 v[118:119], v101
	v_cvt_pk_f32_fp8_e32 v[122:123], v105
	v_pk_fma_f32 v[8:9], v[120:121], v[30:31], v[8:9]
	v_pk_fma_f32 v[116:117], v[246:247], v[30:31], v[116:117]
	v_cvt_pk_f32_fp8_sdwa v[120:121], v101 src0_sel:WORD_1
	v_cvt_pk_f32_fp8_sdwa v[246:247], v105 src0_sel:WORD_1
	v_pk_fma_f32 v[8:9], v[118:119], v[32:33], v[8:9]
	v_pk_fma_f32 v[116:117], v[122:123], v[32:33], v[116:117]
	v_cvt_pk_f32_fp8_e32 v[118:119], v102
	v_cvt_pk_f32_fp8_e32 v[122:123], v106
	v_pk_fma_f32 v[8:9], v[120:121], v[34:35], v[8:9]
	v_pk_fma_f32 v[116:117], v[246:247], v[34:35], v[116:117]
	v_cvt_pk_f32_fp8_sdwa v[120:121], v102 src0_sel:WORD_1
	v_cvt_pk_f32_fp8_sdwa v[246:247], v106 src0_sel:WORD_1
	v_pk_fma_f32 v[8:9], v[118:119], v[36:37], v[8:9]
	v_pk_fma_f32 v[116:117], v[122:123], v[36:37], v[116:117]
	v_cvt_pk_f32_fp8_e32 v[118:119], v103
	v_cvt_pk_f32_fp8_e32 v[122:123], v107
	v_pk_fma_f32 v[8:9], v[120:121], v[38:39], v[8:9]
	v_pk_fma_f32 v[116:117], v[246:247], v[38:39], v[116:117]
	v_cvt_pk_f32_fp8_sdwa v[120:121], v103 src0_sel:WORD_1
	v_cvt_pk_f32_fp8_sdwa v[246:247], v107 src0_sel:WORD_1
	v_pk_fma_f32 v[8:9], v[118:119], v[40:41], v[8:9]
	v_pk_fma_f32 v[116:117], v[122:123], v[40:41], v[116:117]
	v_pk_fma_f32 v[8:9], v[120:121], v[42:43], v[8:9]
	v_pk_fma_f32 v[116:117], v[246:247], v[42:43], v[116:117]
	v_add_f32_e32 v130, v8, v9
	v_add_f32_e32 v131, v116, v117
	v_cndmask_b32_e32 v116, v124, v128, vcc
	v_cndmask_b32_e32 v117, v128, v124, vcc
	v_cndmask_b32_e32 v118, v125, v129, vcc
	v_cndmask_b32_e32 v119, v129, v125, vcc
	v_cndmask_b32_e32 v120, v126, v130, vcc
	v_cndmask_b32_e32 v121, v130, v126, vcc
	v_cndmask_b32_e32 v122, v127, v131, vcc
	v_cndmask_b32_e32 v123, v131, v127, vcc
	v_add_f32_dpp v124, v117, v116 row_half_mirror row_mask:0xf bank_mask:0xf
	v_add_f32_dpp v125, v119, v118 row_half_mirror row_mask:0xf bank_mask:0xf
	v_add_f32_dpp v126, v121, v120 row_half_mirror row_mask:0xf bank_mask:0xf
	v_add_f32_dpp v127, v123, v122 row_half_mirror row_mask:0xf bank_mask:0xf
	v_cndmask_b32_e64 v116, v124, v126, s[34:35]
	v_cndmask_b32_e64 v117, v126, v124, s[34:35]
	v_cndmask_b32_e64 v118, v125, v127, s[34:35]
	v_cndmask_b32_e64 v119, v127, v125, s[34:35]
	s_nop 0
	v_add_f32_dpp v124, v117, v116 quad_perm:[2,3,0,1] row_mask:0xf bank_mask:0xf
	v_add_f32_dpp v125, v119, v118 quad_perm:[2,3,0,1] row_mask:0xf bank_mask:0xf
	v_cndmask_b32_e64 v116, v124, v125, s[30:31]
	v_cndmask_b32_e64 v117, v125, v124, s[30:31]
	s_nop 1
	v_add_f32_dpp v7, v117, v116 quad_perm:[1,0,3,2] row_mask:0xf bank_mask:0xf
	s_lshl_b32 s0, s38, 9
	v_add_u32_e32 v19, s0, v3
	global_store_dword v19, v5, s[46:47]
	global_store_dword v19, v7, s[46:47] offset:256
	s_add_i32 s38, s38, s39
	s_cmp_gt_u32 s38, 0xffff
	s_cbranch_scc1 .Lpu_part_next

.Lpu_tokB_in:
	v_lshlrev_b32_e32 v28, 16, v20
	v_and_b32_e32 v29, 0xffff0000, v20
	v_lshlrev_b32_e32 v30, 16, v21
	v_and_b32_e32 v31, 0xffff0000, v21
	v_lshlrev_b32_e32 v32, 16, v22
	v_and_b32_e32 v33, 0xffff0000, v22
	v_lshlrev_b32_e32 v34, 16, v23
	v_and_b32_e32 v35, 0xffff0000, v23
	v_lshlrev_b32_e32 v36, 16, v24
	v_and_b32_e32 v37, 0xffff0000, v24
	v_lshlrev_b32_e32 v38, 16, v25
	v_and_b32_e32 v39, 0xffff0000, v25
	v_lshlrev_b32_e32 v40, 16, v26
	v_and_b32_e32 v41, 0xffff0000, v26
	v_lshlrev_b32_e32 v42, 16, v27
	v_and_b32_e32 v43, 0xffff0000, v27
	ds_bpermute_b32 v124, v4, v10
	ds_bpermute_b32 v125, v12, v10
	ds_bpermute_b32 v126, v13, v10
	ds_bpermute_b32 v127, v14, v10
	ds_bpermute_b32 v128, v15, v10
	ds_bpermute_b32 v129, v16, v10
	ds_bpermute_b32 v130, v17, v10
	ds_bpermute_b32 v131, v18, v10
	s_waitcnt lgkmcnt(0)
	v_lshl_add_u32 v124, v124, 7, v1
	v_lshl_add_u32 v125, v125, 7, v1
	v_lshl_add_u32 v126, v126, 7, v1
	v_lshl_add_u32 v127, v127, 7, v1
	v_lshl_add_u32 v128, v128, 7, v1
	v_lshl_add_u32 v129, v129, 7, v1
	v_lshl_add_u32 v130, v130, 7, v1
	v_lshl_add_u32 v131, v131, 7, v1
	global_load_dwordx4 v[44:47], v124, s[44:45]
	global_load_dwordx4 v[48:51], v125, s[44:45]
	global_load_dwordx4 v[52:55], v126, s[44:45]
	global_load_dwordx4 v[56:59], v127, s[44:45]
	global_load_dwordx4 v[60:63], v128, s[44:45]
	global_load_dwordx4 v[64:67], v129, s[44:45]
	global_load_dwordx4 v[68:71], v130, s[44:45]
	global_load_dwordx4 v[72:75], v131, s[44:45]
	ds_bpermute_b32 v124, v4, v11
	ds_bpermute_b32 v125, v12, v11
	ds_bpermute_b32 v126, v13, v11
	ds_bpermute_b32 v127, v14, v11
	ds_bpermute_b32 v128, v15, v11
	ds_bpermute_b32 v129, v16, v11
	ds_bpermute_b32 v130, v17, v11
	ds_bpermute_b32 v131, v18, v11
	s_waitcnt lgkmcnt(0)
	v_lshl_add_u32 v124, v124, 7, v1
	v_lshl_add_u32 v125, v125, 7, v1
	v_lshl_add_u32 v126, v126, 7, v1
	v_lshl_add_u32 v127, v127, 7, v1
	v_lshl_add_u32 v128, v128, 7, v1
	v_lshl_add_u32 v129, v129, 7, v1
	v_lshl_add_u32 v130, v130, 7, v1
	v_lshl_add_u32 v131, v131, 7, v1
	global_load_dwordx4 v[76:79], v124, s[44:45]
	global_load_dwordx4 v[80:83], v125, s[44:45]
	global_load_dwordx4 v[84:87], v126, s[44:45]
	global_load_dwordx4 v[88:91], v127, s[44:45]
	global_load_dwordx4 v[92:95], v128, s[44:45]
	global_load_dwordx4 v[96:99], v129, s[44:45]
	global_load_dwordx4 v[100:103], v130, s[44:45]
	global_load_dwordx4 v[104:107], v131, s[44:45]
	s_lshl_b32 s1, s39, 1
	s_add_i32 s1, s1, s38
	s_min_u32 s1, s1, 0xffff
	s_lshl_b32 s0, s1, 9
	v_add_u32_e32 v0, s0, v6
	global_load_dword v10, v0, s[42:43]
	global_load_dword v11, v0, s[42:43] offset:256
	s_lshl_b32 s0, s1, 11
	v_add_u32_e32 v0, s0, v2
	global_load_dwordx4 v[20:23], v0, s[48:49]
	global_load_dwordx4 v[24:27], v0, s[48:49] offset:16
	v_cvt_pk_f32_fp8_e32 v[118:119], v198
	v_cvt_pk_f32_fp8_e32 v[122:123], v202
	v_cvt_pk_f32_fp8_sdwa v[120:121], v198 src0_sel:WORD_1
	v_cvt_pk_f32_fp8_sdwa v[246:247], v202 src0_sel:WORD_1
	v_pk_mul_f32 v[8:9], v[118:119], v[108:109]
	v_pk_mul_f32 v[116:117], v[122:123], v[108:109]
	v_cvt_pk_f32_fp8_e32 v[118:119], v199
	v_cvt_pk_f32_fp8_e32 v[122:123], v203
	v_pk_fma_f32 v[8:9], v[120:121], v[110:111], v[8:9]
	v_pk_fma_f32 v[116:117], v[246:247], v[110:111], v[116:117]
	v_cvt_pk_f32_fp8_sdwa v[120:121], v199 src0_sel:WORD_1
	v_cvt_pk_f32_fp8_sdwa v[246:247], v203 src0_sel:WORD_1
	v_pk_fma_f32 v[8:9], v[118:119], v[112:113], v[8:9]
	v_pk_fma_f32 v[116:117], v[122:123], v[112:113], v[116:117]
	v_cvt_pk_f32_fp8_e32 v[118:119], v200
	v_cvt_pk_f32_fp8_e32 v[122:123], v204
	v_pk_fma_f32 v[8:9], v[120:121], v[114:115], v[8:9]
	v_pk_fma_f32 v[116:117], v[246:247], v[114:115], v[116:117]
	v_cvt_pk_f32_fp8_sdwa v[120:121], v200 src0_sel:WORD_1
	v_cvt_pk_f32_fp8_sdwa v[246:247], v204 src0_sel:WORD_1
	v_pk_fma_f32 v[8:9], v[118:119], v[238:239], v[8:9]
	v_pk_fma_f32 v[116:117], v[122:123], v[238:239], v[116:117]
	v_cvt_pk_f32_fp8_e32 v[118:119], v201
	v_cvt_pk_f32_fp8_e32 v[122:123], v205
	v_pk_fma_f32 v[8:9], v[120:121], v[240:241], v[8:9]
	v_pk_fma_f32 v[116:117], v[246:247], v[240:241], v[116:117]
	v_cvt_pk_f32_fp8_sdwa v[120:121], v201 src0_sel:WORD_1
	v_cvt_pk_f32_fp8_sdwa v[246:247], v205 src0_sel:WORD_1
	v_pk_fma_f32 v[8:9], v[118:119], v[242:243], v[8:9]
	v_pk_fma_f32 v[116:117], v[122:123], v[242:243], v[116:117]
	v_pk_fma_f32 v[8:9], v[120:121], v[244:245], v[8:9]
	v_pk_fma_f32 v[116:117], v[246:247], v[244:245], v[116:117]
	v_add_f32_e32 v124, v8, v9
	v_add_f32_e32 v125, v116, v117
	v_cvt_pk_f32_fp8_e32 v[118:119], v206
	v_cvt_pk_f32_fp8_e32 v[122:123], v210
	v_cvt_pk_f32_fp8_sdwa v[120:121], v206 src0_sel:WORD_1
	v_cvt_pk_f32_fp8_sdwa v[246:247], v210 src0_sel:WORD_1
	v_pk_mul_f32 v[8:9], v[118:119], v[108:109]
	v_pk_mul_f32 v[116:117], v[122:123], v[108:109]
	v_cvt_pk_f32_fp8_e32 v[118:119], v207
	v_cvt_pk_f32_fp8_e32 v[122:123], v211
	v_pk_fma_f32 v[8:9], v[120:121], v[110:111], v[8:9]
	v_pk_fma_f32 v[116:117], v[246:247], v[110:111], v[116:117]
	v_cvt_pk_f32_fp8_sdwa v[120:121], v207 src0_sel:WORD_1
	v_cvt_pk_f32_fp8_sdwa v[246:247], v211 src0_sel:WORD_1
	v_pk_fma_f32 v[8:9], v[118:119], v[112:113], v[8:9]
	v_pk_fma_f32 v[116:117], v[122:123], v[112:113], v[116:117]
	v_cvt_pk_f32_fp8_e32 v[118:119], v208
	v_cvt_pk_f32_fp8_e32 v[122:123], v212
	v_pk_fma_f32 v[8:9], v[120:121], v[114:115], v[8:9]
	v_pk_fma_f32 v[116:117], v[246:247], v[114:115], v[116:117]
	v_cvt_pk_f32_fp8_sdwa v[120:121], v208 src0_sel:WORD_1
	v_cvt_pk_f32_fp8_sdwa v[246:247], v212 src0_sel:WORD_1
	v_pk_fma_f32 v[8:9], v[118:119], v[238:239], v[8:9]
	v_pk_fma_f32 v[116:117], v[122:123], v[238:239], v[116:117]
	v_cvt_pk_f32_fp8_e32 v[118:119], v209
	v_cvt_pk_f32_fp8_e32 v[122:123], v213
	v_pk_fma_f32 v[8:9], v[120:121], v[240:241], v[8:9]
	v_pk_fma_f32 v[116:117], v[246:247], v[240:241], v[116:117]
	v_cvt_pk_f32_fp8_sdwa v[120:121], v209 src0_sel:WORD_1
	v_cvt_pk_f32_fp8_sdwa v[246:247], v213 src0_sel:WORD_1
	v_pk_fma_f32 v[8:9], v[118:119], v[242:243], v[8:9]
	v_pk_fma_f32 v[116:117], v[122:123], v[242:243], v[116:117]
	v_pk_fma_f32 v[8:9], v[120:121], v[244:245], v[8:9]
	v_pk_fma_f32 v[116:117], v[246:247], v[244:245], v[116:117]
	v_add_f32_e32 v126, v8, v9
	v_add_f32_e32 v127, v116, v117
	v_cvt_pk_f32_fp8_e32 v[118:119], v214
	v_cvt_pk_f32_fp8_e32 v[122:123], v218
	v_cvt_pk_f32_fp8_sdwa v[120:121], v214 src0_sel:WORD_1
	v_cvt_pk_f32_fp8_sdwa v[246:247], v218 src0_sel:WORD_1
	v_pk_mul_f32 v[8:9], v[118:119], v[108:109]
	v_pk_mul_f32 v[116:117], v[122:123], v[108:109]
	v_cvt_pk_f32_fp8_e32 v[118:119], v215
	v_cvt_pk_f32_fp8_e32 v[122:123], v219
	v_pk_fma_f32 v[8:9], v[120:121], v[110:111], v[8:9]
	v_pk_fma_f32 v[116:117], v[246:247], v[110:111], v[116:117]
	v_cvt_pk_f32_fp8_sdwa v[120:121], v215 src0_sel:WORD_1
	v_cvt_pk_f32_fp8_sdwa v[246:247], v219 src0_sel:WORD_1
	v_pk_fma_f32 v[8:9], v[118:119], v[112:113], v[8:9]
	v_pk_fma_f32 v[116:117], v[122:123], v[112:113], v[116:117]
	v_cvt_pk_f32_fp8_e32 v[118:119], v216
	v_cvt_pk_f32_fp8_e32 v[122:123], v220
	v_pk_fma_f32 v[8:9], v[120:121], v[114:115], v[8:9]
	v_pk_fma_f32 v[116:117], v[246:247], v[114:115], v[116:117]
	v_cvt_pk_f32_fp8_sdwa v[120:121], v216 src0_sel:WORD_1
	v_cvt_pk_f32_fp8_sdwa v[246:247], v220 src0_sel:WORD_1
	v_pk_fma_f32 v[8:9], v[118:119], v[238:239], v[8:9]
	v_pk_fma_f32 v[116:117], v[122:123], v[238:239], v[116:117]
	v_cvt_pk_f32_fp8_e32 v[118:119], v217
	v_cvt_pk_f32_fp8_e32 v[122:123], v221
	v_pk_fma_f32 v[8:9], v[120:121], v[240:241], v[8:9]
	v_pk_fma_f32 v[116:117], v[246:247], v[240:241], v[116:117]
	v_cvt_pk_f32_fp8_sdwa v[120:121], v217 src0_sel:WORD_1
	v_cvt_pk_f32_fp8_sdwa v[246:247], v221 src0_sel:WORD_1
	v_pk_fma_f32 v[8:9], v[118:119], v[242:243], v[8:9]
	v_pk_fma_f32 v[116:117], v[122:123], v[242:243], v[116:117]
	v_pk_fma_f32 v[8:9], v[120:121], v[244:245], v[8:9]
	v_pk_fma_f32 v[116:117], v[246:247], v[244:245], v[116:117]
	v_add_f32_e32 v128, v8, v9
	v_add_f32_e32 v129, v116, v117
	v_cvt_pk_f32_fp8_e32 v[118:119], v222
	v_cvt_pk_f32_fp8_e32 v[122:123], v226
	v_cvt_pk_f32_fp8_sdwa v[120:121], v222 src0_sel:WORD_1
	v_cvt_pk_f32_fp8_sdwa v[246:247], v226 src0_sel:WORD_1
	v_pk_mul_f32 v[8:9], v[118:119], v[108:109]
	v_pk_mul_f32 v[116:117], v[122:123], v[108:109]
	v_cvt_pk_f32_fp8_e32 v[118:119], v223
	v_cvt_pk_f32_fp8_e32 v[122:123], v227
	v_pk_fma_f32 v[8:9], v[120:121], v[110:111], v[8:9]
	v_pk_fma_f32 v[116:117], v[246:247], v[110:111], v[116:117]
	v_cvt_pk_f32_fp8_sdwa v[120:121], v223 src0_sel:WORD_1
	v_cvt_pk_f32_fp8_sdwa v[246:247], v227 src0_sel:WORD_1
	v_pk_fma_f32 v[8:9], v[118:119], v[112:113], v[8:9]
	v_pk_fma_f32 v[116:117], v[122:123], v[112:113], v[116:117]
	v_cvt_pk_f32_fp8_e32 v[118:119], v224
	v_cvt_pk_f32_fp8_e32 v[122:123], v228
	v_pk_fma_f32 v[8:9], v[120:121], v[114:115], v[8:9]
	v_pk_fma_f32 v[116:117], v[246:247], v[114:115], v[116:117]
	v_cvt_pk_f32_fp8_sdwa v[120:121], v224 src0_sel:WORD_1
	v_cvt_pk_f32_fp8_sdwa v[246:247], v228 src0_sel:WORD_1
	v_pk_fma_f32 v[8:9], v[118:119], v[238:239], v[8:9]
	v_pk_fma_f32 v[116:117], v[122:123], v[238:239], v[116:117]
	v_cvt_pk_f32_fp8_e32 v[118:119], v225
	v_cvt_pk_f32_fp8_e32 v[122:123], v229
	v_pk_fma_f32 v[8:9], v[120:121], v[240:241], v[8:9]
	v_pk_fma_f32 v[116:117], v[246:247], v[240:241], v[116:117]
	v_cvt_pk_f32_fp8_sdwa v[120:121], v225 src0_sel:WORD_1
	v_cvt_pk_f32_fp8_sdwa v[246:247], v229 src0_sel:WORD_1
	v_pk_fma_f32 v[8:9], v[118:119], v[242:243], v[8:9]
	v_pk_fma_f32 v[116:117], v[122:123], v[242:243], v[116:117]
	v_pk_fma_f32 v[8:9], v[120:121], v[244:245], v[8:9]
	v_pk_fma_f32 v[116:117], v[246:247], v[244:245], v[116:117]
	v_add_f32_e32 v130, v8, v9
	v_add_f32_e32 v131, v116, v117
	v_cndmask_b32_e32 v116, v124, v128, vcc
	v_cndmask_b32_e32 v117, v128, v124, vcc
	v_cndmask_b32_e32 v118, v125, v129, vcc
	v_cndmask_b32_e32 v119, v129, v125, vcc
	v_cndmask_b32_e32 v120, v126, v130, vcc
	v_cndmask_b32_e32 v121, v130, v126, vcc
	v_cndmask_b32_e32 v122, v127, v131, vcc
	v_cndmask_b32_e32 v123, v131, v127, vcc
	v_add_f32_dpp v124, v117, v116 row_half_mirror row_mask:0xf bank_mask:0xf
	v_add_f32_dpp v125, v119, v118 row_half_mirror row_mask:0xf bank_mask:0xf
	v_add_f32_dpp v126, v121, v120 row_half_mirror row_mask:0xf bank_mask:0xf
	v_add_f32_dpp v127, v123, v122 row_half_mirror row_mask:0xf bank_mask:0xf
	v_cndmask_b32_e64 v116, v124, v126, s[34:35]
	v_cndmask_b32_e64 v117, v126, v124, s[34:35]
	v_cndmask_b32_e64 v118, v125, v127, s[34:35]
	v_cndmask_b32_e64 v119, v127, v125, s[34:35]
	s_nop 0
	v_add_f32_dpp v124, v117, v116 quad_perm:[2,3,0,1] row_mask:0xf bank_mask:0xf
	v_add_f32_dpp v125, v119, v118 quad_perm:[2,3,0,1] row_mask:0xf bank_mask:0xf
	v_cndmask_b32_e64 v116, v124, v125, s[30:31]
	v_cndmask_b32_e64 v117, v125, v124, s[30:31]
	s_nop 1
	v_add_f32_dpp v5, v117, v116 quad_perm:[1,0,3,2] row_mask:0xf bank_mask:0xf
	v_cvt_pk_f32_fp8_e32 v[118:119], v230
	v_cvt_pk_f32_fp8_e32 v[122:123], v234
	v_cvt_pk_f32_fp8_sdwa v[120:121], v230 src0_sel:WORD_1
	v_cvt_pk_f32_fp8_sdwa v[246:247], v234 src0_sel:WORD_1
	v_pk_mul_f32 v[8:9], v[118:119], v[108:109]
	v_pk_mul_f32 v[116:117], v[122:123], v[108:109]
	v_cvt_pk_f32_fp8_e32 v[118:119], v231
	v_cvt_pk_f32_fp8_e32 v[122:123], v235
	v_pk_fma_f32 v[8:9], v[120:121], v[110:111], v[8:9]
	v_pk_fma_f32 v[116:117], v[246:247], v[110:111], v[116:117]
	v_cvt_pk_f32_fp8_sdwa v[120:121], v231 src0_sel:WORD_1
	v_cvt_pk_f32_fp8_sdwa v[246:247], v235 src0_sel:WORD_1
	v_pk_fma_f32 v[8:9], v[118:119], v[112:113], v[8:9]
	v_pk_fma_f32 v[116:117], v[122:123], v[112:113], v[116:117]
	v_cvt_pk_f32_fp8_e32 v[118:119], v232
	v_cvt_pk_f32_fp8_e32 v[122:123], v236
	v_pk_fma_f32 v[8:9], v[120:121], v[114:115], v[8:9]
	v_pk_fma_f32 v[116:117], v[246:247], v[114:115], v[116:117]
	v_cvt_pk_f32_fp8_sdwa v[120:121], v232 src0_sel:WORD_1
	v_cvt_pk_f32_fp8_sdwa v[246:247], v236 src0_sel:WORD_1
	v_pk_fma_f32 v[8:9], v[118:119], v[238:239], v[8:9]
	v_pk_fma_f32 v[116:117], v[122:123], v[238:239], v[116:117]
	v_cvt_pk_f32_fp8_e32 v[118:119], v233
	v_cvt_pk_f32_fp8_e32 v[122:123], v237
	v_pk_fma_f32 v[8:9], v[120:121], v[240:241], v[8:9]
	v_pk_fma_f32 v[116:117], v[246:247], v[240:241], v[116:117]
	v_cvt_pk_f32_fp8_sdwa v[120:121], v233 src0_sel:WORD_1
	v_cvt_pk_f32_fp8_sdwa v[246:247], v237 src0_sel:WORD_1
	v_pk_fma_f32 v[8:9], v[118:119], v[242:243], v[8:9]
	v_pk_fma_f32 v[116:117], v[122:123], v[242:243], v[116:117]
	v_pk_fma_f32 v[8:9], v[120:121], v[244:245], v[8:9]
	v_pk_fma_f32 v[116:117], v[246:247], v[244:245], v[116:117]
	v_add_f32_e32 v124, v8, v9
	v_add_f32_e32 v125, v116, v117
	v_cvt_pk_f32_fp8_e32 v[118:119], v138
	v_cvt_pk_f32_fp8_e32 v[122:123], v142
	v_cvt_pk_f32_fp8_sdwa v[120:121], v138 src0_sel:WORD_1
	v_cvt_pk_f32_fp8_sdwa v[246:247], v142 src0_sel:WORD_1
	v_pk_mul_f32 v[8:9], v[118:119], v[108:109]
	v_pk_mul_f32 v[116:117], v[122:123], v[108:109]
	v_cvt_pk_f32_fp8_e32 v[118:119], v139
	v_cvt_pk_f32_fp8_e32 v[122:123], v143
	v_pk_fma_f32 v[8:9], v[120:121], v[110:111], v[8:9]
	v_pk_fma_f32 v[116:117], v[246:247], v[110:111], v[116:117]
	v_cvt_pk_f32_fp8_sdwa v[120:121], v139 src0_sel:WORD_1
	v_cvt_pk_f32_fp8_sdwa v[246:247], v143 src0_sel:WORD_1
	v_pk_fma_f32 v[8:9], v[118:119], v[112:113], v[8:9]
	v_pk_fma_f32 v[116:117], v[122:123], v[112:113], v[116:117]
	v_cvt_pk_f32_fp8_e32 v[118:119], v140
	v_cvt_pk_f32_fp8_e32 v[122:123], v144
	v_pk_fma_f32 v[8:9], v[120:121], v[114:115], v[8:9]
	v_pk_fma_f32 v[116:117], v[246:247], v[114:115], v[116:117]
	v_cvt_pk_f32_fp8_sdwa v[120:121], v140 src0_sel:WORD_1
	v_cvt_pk_f32_fp8_sdwa v[246:247], v144 src0_sel:WORD_1
	v_pk_fma_f32 v[8:9], v[118:119], v[238:239], v[8:9]
	v_pk_fma_f32 v[116:117], v[122:123], v[238:239], v[116:117]
	v_cvt_pk_f32_fp8_e32 v[118:119], v141
	v_cvt_pk_f32_fp8_e32 v[122:123], v145
	v_pk_fma_f32 v[8:9], v[120:121], v[240:241], v[8:9]
	v_pk_fma_f32 v[116:117], v[246:247], v[240:241], v[116:117]
	v_cvt_pk_f32_fp8_sdwa v[120:121], v141 src0_sel:WORD_1
	v_cvt_pk_f32_fp8_sdwa v[246:247], v145 src0_sel:WORD_1
	v_pk_fma_f32 v[8:9], v[118:119], v[242:243], v[8:9]
	v_pk_fma_f32 v[116:117], v[122:123], v[242:243], v[116:117]
	v_pk_fma_f32 v[8:9], v[120:121], v[244:245], v[8:9]
	v_pk_fma_f32 v[116:117], v[246:247], v[244:245], v[116:117]
	v_add_f32_e32 v126, v8, v9
	v_add_f32_e32 v127, v116, v117
	v_cvt_pk_f32_fp8_e32 v[118:119], v146
	v_cvt_pk_f32_fp8_e32 v[122:123], v150
	v_cvt_pk_f32_fp8_sdwa v[120:121], v146 src0_sel:WORD_1
	v_cvt_pk_f32_fp8_sdwa v[246:247], v150 src0_sel:WORD_1
	v_pk_mul_f32 v[8:9], v[118:119], v[108:109]
	v_pk_mul_f32 v[116:117], v[122:123], v[108:109]
	v_cvt_pk_f32_fp8_e32 v[118:119], v147
	v_cvt_pk_f32_fp8_e32 v[122:123], v151
	v_pk_fma_f32 v[8:9], v[120:121], v[110:111], v[8:9]
	v_pk_fma_f32 v[116:117], v[246:247], v[110:111], v[116:117]
	v_cvt_pk_f32_fp8_sdwa v[120:121], v147 src0_sel:WORD_1
	v_cvt_pk_f32_fp8_sdwa v[246:247], v151 src0_sel:WORD_1
	v_pk_fma_f32 v[8:9], v[118:119], v[112:113], v[8:9]
	v_pk_fma_f32 v[116:117], v[122:123], v[112:113], v[116:117]
	v_cvt_pk_f32_fp8_e32 v[118:119], v148
	v_cvt_pk_f32_fp8_e32 v[122:123], v152
	v_pk_fma_f32 v[8:9], v[120:121], v[114:115], v[8:9]
	v_pk_fma_f32 v[116:117], v[246:247], v[114:115], v[116:117]
	v_cvt_pk_f32_fp8_sdwa v[120:121], v148 src0_sel:WORD_1
	v_cvt_pk_f32_fp8_sdwa v[246:247], v152 src0_sel:WORD_1
	v_pk_fma_f32 v[8:9], v[118:119], v[238:239], v[8:9]
	v_pk_fma_f32 v[116:117], v[122:123], v[238:239], v[116:117]
	v_cvt_pk_f32_fp8_e32 v[118:119], v149
	v_cvt_pk_f32_fp8_e32 v[122:123], v153
	v_pk_fma_f32 v[8:9], v[120:121], v[240:241], v[8:9]
	v_pk_fma_f32 v[116:117], v[246:247], v[240:241], v[116:117]
	v_cvt_pk_f32_fp8_sdwa v[120:121], v149 src0_sel:WORD_1
	v_cvt_pk_f32_fp8_sdwa v[246:247], v153 src0_sel:WORD_1
	v_pk_fma_f32 v[8:9], v[118:119], v[242:243], v[8:9]
	v_pk_fma_f32 v[116:117], v[122:123], v[242:243], v[116:117]
	v_pk_fma_f32 v[8:9], v[120:121], v[244:245], v[8:9]
	v_pk_fma_f32 v[116:117], v[246:247], v[244:245], v[116:117]
	v_add_f32_e32 v128, v8, v9
	v_add_f32_e32 v129, v116, v117
	v_cvt_pk_f32_fp8_e32 v[118:119], v154
	v_cvt_pk_f32_fp8_e32 v[122:123], v158
	v_cvt_pk_f32_fp8_sdwa v[120:121], v154 src0_sel:WORD_1
	v_cvt_pk_f32_fp8_sdwa v[246:247], v158 src0_sel:WORD_1
	v_pk_mul_f32 v[8:9], v[118:119], v[108:109]
	v_pk_mul_f32 v[116:117], v[122:123], v[108:109]
	v_cvt_pk_f32_fp8_e32 v[118:119], v155
	v_cvt_pk_f32_fp8_e32 v[122:123], v159
	v_pk_fma_f32 v[8:9], v[120:121], v[110:111], v[8:9]
	v_pk_fma_f32 v[116:117], v[246:247], v[110:111], v[116:117]
	v_cvt_pk_f32_fp8_sdwa v[120:121], v155 src0_sel:WORD_1
	v_cvt_pk_f32_fp8_sdwa v[246:247], v159 src0_sel:WORD_1
	v_pk_fma_f32 v[8:9], v[118:119], v[112:113], v[8:9]
	v_pk_fma_f32 v[116:117], v[122:123], v[112:113], v[116:117]
	v_cvt_pk_f32_fp8_e32 v[118:119], v156
	v_cvt_pk_f32_fp8_e32 v[122:123], v160
	v_pk_fma_f32 v[8:9], v[120:121], v[114:115], v[8:9]
	v_pk_fma_f32 v[116:117], v[246:247], v[114:115], v[116:117]
	v_cvt_pk_f32_fp8_sdwa v[120:121], v156 src0_sel:WORD_1
	v_cvt_pk_f32_fp8_sdwa v[246:247], v160 src0_sel:WORD_1
	v_pk_fma_f32 v[8:9], v[118:119], v[238:239], v[8:9]
	v_pk_fma_f32 v[116:117], v[122:123], v[238:239], v[116:117]
	v_cvt_pk_f32_fp8_e32 v[118:119], v157
	v_cvt_pk_f32_fp8_e32 v[122:123], v161
	v_pk_fma_f32 v[8:9], v[120:121], v[240:241], v[8:9]
	v_pk_fma_f32 v[116:117], v[246:247], v[240:241], v[116:117]
	v_cvt_pk_f32_fp8_sdwa v[120:121], v157 src0_sel:WORD_1
	v_cvt_pk_f32_fp8_sdwa v[246:247], v161 src0_sel:WORD_1
	v_pk_fma_f32 v[8:9], v[118:119], v[242:243], v[8:9]
	v_pk_fma_f32 v[116:117], v[122:123], v[242:243], v[116:117]
	v_pk_fma_f32 v[8:9], v[120:121], v[244:245], v[8:9]
	v_pk_fma_f32 v[116:117], v[246:247], v[244:245], v[116:117]
	v_add_f32_e32 v130, v8, v9
	v_add_f32_e32 v131, v116, v117
	v_cndmask_b32_e32 v116, v124, v128, vcc
	v_cndmask_b32_e32 v117, v128, v124, vcc
	v_cndmask_b32_e32 v118, v125, v129, vcc
	v_cndmask_b32_e32 v119, v129, v125, vcc
	v_cndmask_b32_e32 v120, v126, v130, vcc
	v_cndmask_b32_e32 v121, v130, v126, vcc
	v_cndmask_b32_e32 v122, v127, v131, vcc
	v_cndmask_b32_e32 v123, v131, v127, vcc
	v_add_f32_dpp v124, v117, v116 row_half_mirror row_mask:0xf bank_mask:0xf
	v_add_f32_dpp v125, v119, v118 row_half_mirror row_mask:0xf bank_mask:0xf
	v_add_f32_dpp v126, v121, v120 row_half_mirror row_mask:0xf bank_mask:0xf
	v_add_f32_dpp v127, v123, v122 row_half_mirror row_mask:0xf bank_mask:0xf
	v_cndmask_b32_e64 v116, v124, v126, s[34:35]
	v_cndmask_b32_e64 v117, v126, v124, s[34:35]
	v_cndmask_b32_e64 v118, v125, v127, s[34:35]
	v_cndmask_b32_e64 v119, v127, v125, s[34:35]
	s_nop 0
	v_add_f32_dpp v124, v117, v116 quad_perm:[2,3,0,1] row_mask:0xf bank_mask:0xf
	v_add_f32_dpp v125, v119, v118 quad_perm:[2,3,0,1] row_mask:0xf bank_mask:0xf
	v_cndmask_b32_e64 v116, v124, v125, s[30:31]
	v_cndmask_b32_e64 v117, v125, v124, s[30:31]
	s_nop 1
	v_add_f32_dpp v7, v117, v116 quad_perm:[1,0,3,2] row_mask:0xf bank_mask:0xf
	s_lshl_b32 s0, s38, 9
	v_add_u32_e32 v19, s0, v3
	global_store_dword v19, v5, s[46:47]
	global_store_dword v19, v7, s[46:47] offset:256
	s_add_i32 s38, s38, s39
	s_cmp_gt_u32 s38, 0xffff
	s_cbranch_scc1 .Lpu_part_next
	s_branch .Lpu_tokA

.LBB0_127:
	v_add_u32_e32 v210, s21, v157
	v_add3_u32 v206, v210, v152, v153
	v_add3_u32 v222, v210, v154, v153
	ds_read_b128 v[146:149], v206 offset:32768
	ds_read_b128 v[206:209], v206 offset:36864
	ds_read_b128 v[210:213], v222
	ds_read_b128 v[214:217], v222 offset:4096
	ds_read_b128 v[218:221], v222 offset:8192
	ds_read_b128 v[222:225], v222 offset:12288
	s_setprio 1
	s_waitcnt lgkmcnt(3)
	v_mfma_f32_32x32x16_bf16 v[112:127], v[146:149], v[210:213], v[112:127]
	s_waitcnt lgkmcnt(2)
	v_mfma_f32_32x32x16_bf16 v[96:111], v[146:149], v[214:217], v[96:111]
	s_waitcnt lgkmcnt(1)
	v_mfma_f32_32x32x16_bf16 v[48:63], v[146:149], v[218:221], v[48:63]
	s_waitcnt lgkmcnt(0)
	v_mfma_f32_32x32x16_bf16 v[32:47], v[146:149], v[222:225], v[32:47]
	v_mfma_f32_32x32x16_bf16 v[80:95], v[206:209], v[210:213], v[80:95]
	v_mfma_f32_32x32x16_bf16 v[64:79], v[206:209], v[214:217], v[64:79]
	v_mfma_f32_32x32x16_bf16 v[16:31], v[206:209], v[218:221], v[16:31]
	v_mfma_f32_32x32x16_bf16 v[0:15], v[206:209], v[222:225], v[0:15]
	s_setprio 0
	s_waitcnt vmcnt(0)
	s_add_u32 s48, s48, 0x80
	s_addc_u32 s49, s49, 0
	s_cmpk_eq_i32 s48, 0x800
	s_waitcnt vmcnt(0)
	s_barrier
	s_cbranch_scc1 .LBB0_134

.LBB0_130:
	v_lshl_add_u64 v[146:147], v[142:143], 0, s[48:49]
	v_add_u32_e32 v207, s21, v155
	v_add3_u32 v212, v207, v152, v153
	v_add3_u32 v207, v207, v154, v153
	ds_read_b128 v[208:211], v212 offset:32768
	ds_read_b128 v[212:215], v212 offset:36864
	ds_read_b128 v[216:219], v207
	ds_read_b128 v[220:223], v207 offset:4096
	ds_read_b128 v[224:227], v207 offset:8192
	ds_read_b128 v[228:231], v207 offset:12288
	s_setprio 1
	s_waitcnt lgkmcnt(3)
	v_mfma_f32_32x32x16_bf16 v[112:127], v[208:211], v[216:219], v[112:127]
	s_waitcnt lgkmcnt(2)
	v_mfma_f32_32x32x16_bf16 v[96:111], v[208:211], v[220:223], v[96:111]
	s_waitcnt lgkmcnt(1)
	v_mfma_f32_32x32x16_bf16 v[48:63], v[208:211], v[224:227], v[48:63]
	s_waitcnt lgkmcnt(0)
	v_mfma_f32_32x32x16_bf16 v[32:47], v[208:211], v[228:231], v[32:47]
	v_mfma_f32_32x32x16_bf16 v[80:95], v[212:215], v[216:219], v[80:95]
	v_mfma_f32_32x32x16_bf16 v[64:79], v[212:215], v[220:223], v[64:79]
	v_mfma_f32_32x32x16_bf16 v[16:31], v[212:215], v[224:227], v[16:31]
	v_mfma_f32_32x32x16_bf16 v[0:15], v[212:215], v[228:231], v[0:15]
	s_setprio 0
	v_cndmask_b32_e64 v207, 0, 1, s[50:51]
	v_cmp_ne_u32_e64 s[38:39], 1, v207
	s_andn2_b64 vcc, exec, s[50:51]
	s_cbranch_vccnz .LBB0_132
	s_mov_b64 s[24:25], 0x8bcc080
	v_lshl_add_u64 v[148:149], v[148:149], 0, s[24:25]
	s_mov_b64 s[24:25], 0x1c00080
	v_lshl_add_u64 v[208:209], v[146:147], 0, s[24:25]
	s_mov_b64 s[24:25], 0x1c20080
	v_add_u32_e32 v207, 0x6000, v206
	v_lshl_add_u64 v[210:211], v[146:147], 0, s[24:25]
	v_readfirstlane_b32 s24, v207
	s_mov_b32 m0, s24
	s_movk_i32 s25, 0x1000
	global_load_lds_dwordx4 v[148:149], off
	v_add_u32_e32 v148, 0x8000, v206
	s_nop 0
	v_readfirstlane_b32 s24, v148
	v_add_u32_e32 v148, 0xa000, v206
	s_mov_b32 m0, s24
	v_readfirstlane_b32 s24, v148
	global_load_lds_dwordx4 v[208:209], off
	s_mov_b32 m0, s24
	s_nop 0
	global_load_lds_dwordx4 v[210:211], off
.LBB0_132:
	v_add_u32_e32 v148, s21, v156
	v_add3_u32 v149, v148, v152, v153
	v_add3_u32 v148, v148, v154, v153
	ds_read_b128 v[208:211], v149 offset:32768
	ds_read_b128 v[212:215], v149 offset:36864
	ds_read_b128 v[216:219], v148
	ds_read_b128 v[220:223], v148 offset:4096
	ds_read_b128 v[224:227], v148 offset:8192
	ds_read_b128 v[228:231], v148 offset:12288
	s_setprio 1
	s_waitcnt lgkmcnt(3)
	v_mfma_f32_32x32x16_bf16 v[112:127], v[208:211], v[216:219], v[112:127]
	s_waitcnt lgkmcnt(2)
	v_mfma_f32_32x32x16_bf16 v[96:111], v[208:211], v[220:223], v[96:111]
	s_waitcnt lgkmcnt(1)
	v_mfma_f32_32x32x16_bf16 v[48:63], v[208:211], v[224:227], v[48:63]
	s_waitcnt lgkmcnt(0)
	v_mfma_f32_32x32x16_bf16 v[32:47], v[208:211], v[228:231], v[32:47]
	v_mfma_f32_32x32x16_bf16 v[80:95], v[212:215], v[216:219], v[80:95]
	v_mfma_f32_32x32x16_bf16 v[64:79], v[212:215], v[220:223], v[64:79]
	v_mfma_f32_32x32x16_bf16 v[16:31], v[212:215], v[224:227], v[16:31]
	v_mfma_f32_32x32x16_bf16 v[0:15], v[212:215], v[228:231], v[0:15]
	s_setprio 0
	s_and_b64 vcc, exec, s[38:39]
	s_cbranch_vccnz .LBB0_127
	s_mov_b64 s[24:25], 0x1c40080
	v_lshl_add_u64 v[148:149], v[146:147], 0, s[24:25]
	s_mov_b64 s[24:25], 0x1c60080
	v_add_u32_e32 v207, 0xc000, v206
	v_lshl_add_u64 v[146:147], v[146:147], 0, s[24:25]
	v_readfirstlane_b32 s24, v207
	s_mov_b32 m0, s24
	s_movk_i32 s25, 0x1000
	global_load_lds_dwordx4 v[148:149], off
	v_add_u32_e32 v148, 0xe000, v206
	s_nop 0
	v_readfirstlane_b32 s24, v148
	s_mov_b32 m0, s24
	s_nop 0
	global_load_lds_dwordx4 v[146:147], off
	s_branch .LBB0_127

.LBB0_175:
	v_add_u32_e32 v148, s1, v201
	v_add3_u32 v149, v148, v160, v161
	v_add3_u32 v148, v148, v198, v161
	ds_read_b128 v[144:147], v149 offset:32768
	ds_read_b128 v[154:157], v149 offset:36864
	ds_read_b128 v[214:217], v148
	ds_read_b128 v[218:221], v148 offset:4096
	ds_read_b128 v[222:225], v148 offset:8192
	ds_read_b128 v[226:229], v148 offset:12288
	s_setprio 1
	s_waitcnt lgkmcnt(3)
	v_mfma_f32_32x32x16_bf16 v[112:127], v[144:147], v[214:217], v[112:127]
	s_waitcnt lgkmcnt(2)
	v_mfma_f32_32x32x16_bf16 v[96:111], v[144:147], v[218:221], v[96:111]
	s_waitcnt lgkmcnt(1)
	v_mfma_f32_32x32x16_bf16 v[48:63], v[144:147], v[222:225], v[48:63]
	s_waitcnt lgkmcnt(0)
	v_mfma_f32_32x32x16_bf16 v[32:47], v[144:147], v[226:229], v[32:47]
	v_mfma_f32_32x32x16_bf16 v[80:95], v[154:157], v[214:217], v[80:95]
	v_mfma_f32_32x32x16_bf16 v[64:79], v[154:157], v[218:221], v[64:79]
	v_mfma_f32_32x32x16_bf16 v[16:31], v[154:157], v[222:225], v[16:31]
	v_mfma_f32_32x32x16_bf16 v[0:15], v[154:157], v[226:229], v[0:15]
	s_setprio 0
	s_waitcnt vmcnt(0)
	s_add_u32 s54, s54, 0x80
	s_addc_u32 s55, s55, 0
	s_cmpk_eq_i32 s54, 0x800
	s_waitcnt vmcnt(0)
	s_barrier
	s_cbranch_scc1 .LBB0_182

.LBB0_178:
	v_lshl_add_u64 v[144:145], v[150:151], 0, s[54:55]
	v_add_u32_e32 v149, s1, v199
	v_add3_u32 v214, v149, v160, v161
	v_add3_u32 v149, v149, v198, v161
	ds_read_b128 v[154:157], v214 offset:32768
	ds_read_b128 v[214:217], v214 offset:36864
	ds_read_b128 v[218:221], v149
	ds_read_b128 v[222:225], v149 offset:4096
	ds_read_b128 v[226:229], v149 offset:8192
	ds_read_b128 v[230:233], v149 offset:12288
	s_setprio 1
	s_waitcnt lgkmcnt(3)
	v_mfma_f32_32x32x16_bf16 v[112:127], v[154:157], v[218:221], v[112:127]
	s_waitcnt lgkmcnt(2)
	v_mfma_f32_32x32x16_bf16 v[96:111], v[154:157], v[222:225], v[96:111]
	s_waitcnt lgkmcnt(1)
	v_mfma_f32_32x32x16_bf16 v[48:63], v[154:157], v[226:229], v[48:63]
	s_waitcnt lgkmcnt(0)
	v_mfma_f32_32x32x16_bf16 v[32:47], v[154:157], v[230:233], v[32:47]
	v_mfma_f32_32x32x16_bf16 v[80:95], v[214:217], v[218:221], v[80:95]
	v_mfma_f32_32x32x16_bf16 v[64:79], v[214:217], v[222:225], v[64:79]
	v_mfma_f32_32x32x16_bf16 v[16:31], v[214:217], v[226:229], v[16:31]
	v_mfma_f32_32x32x16_bf16 v[0:15], v[214:217], v[230:233], v[0:15]
	s_setprio 0
	v_cndmask_b32_e64 v149, 0, 1, s[56:57]
	v_cmp_ne_u32_e64 s[38:39], 1, v149
	s_andn2_b64 vcc, exec, s[56:57]
	s_cbranch_vccnz .LBB0_180
	s_mov_b64 s[20:21], 0x2dfcc080
	v_lshl_add_u64 v[146:147], v[146:147], 0, s[20:21]
	s_mov_b64 s[20:21], 0x1600080
	v_lshl_add_u64 v[154:155], v[144:145], 0, s[20:21]
	s_mov_b64 s[20:21], 0x1620080
	v_add_u32_e32 v149, 0x6000, v148
	v_lshl_add_u64 v[156:157], v[144:145], 0, s[20:21]
	v_readfirstlane_b32 s20, v149
	s_mov_b32 m0, s20
	s_nop 0
	global_load_lds_dwordx4 v[146:147], off
	v_add_u32_e32 v146, 0x8000, v148
	s_nop 0
	v_readfirstlane_b32 s20, v146
	v_add_u32_e32 v146, 0xa000, v148
	s_mov_b32 m0, s20
	v_readfirstlane_b32 s20, v146
	global_load_lds_dwordx4 v[154:155], off
	s_mov_b32 m0, s20
	s_nop 0
	global_load_lds_dwordx4 v[156:157], off
.LBB0_180:
	v_add_u32_e32 v146, s1, v200
	v_add3_u32 v147, v146, v160, v161
	v_add3_u32 v146, v146, v198, v161
	ds_read_b128 v[154:157], v147 offset:32768
	ds_read_b128 v[214:217], v147 offset:36864
	ds_read_b128 v[218:221], v146
	ds_read_b128 v[222:225], v146 offset:4096
	ds_read_b128 v[226:229], v146 offset:8192
	ds_read_b128 v[230:233], v146 offset:12288
	s_setprio 1
	s_waitcnt lgkmcnt(3)
	v_mfma_f32_32x32x16_bf16 v[112:127], v[154:157], v[218:221], v[112:127]
	s_waitcnt lgkmcnt(2)
	v_mfma_f32_32x32x16_bf16 v[96:111], v[154:157], v[222:225], v[96:111]
	s_waitcnt lgkmcnt(1)
	v_mfma_f32_32x32x16_bf16 v[48:63], v[154:157], v[226:229], v[48:63]
	s_waitcnt lgkmcnt(0)
	v_mfma_f32_32x32x16_bf16 v[32:47], v[154:157], v[230:233], v[32:47]
	v_mfma_f32_32x32x16_bf16 v[80:95], v[214:217], v[218:221], v[80:95]
	v_mfma_f32_32x32x16_bf16 v[64:79], v[214:217], v[222:225], v[64:79]
	v_mfma_f32_32x32x16_bf16 v[16:31], v[214:217], v[226:229], v[16:31]
	v_mfma_f32_32x32x16_bf16 v[0:15], v[214:217], v[230:233], v[0:15]
	s_setprio 0
	s_and_b64 vcc, exec, s[38:39]
	s_cbranch_vccnz .LBB0_175
	s_mov_b64 s[20:21], 0x1640080
	v_lshl_add_u64 v[146:147], v[144:145], 0, s[20:21]
	s_mov_b64 s[20:21], 0x1660080
	v_add_u32_e32 v149, 0xc000, v148
	v_lshl_add_u64 v[144:145], v[144:145], 0, s[20:21]
	v_readfirstlane_b32 s20, v149
	s_mov_b32 m0, s20
	s_nop 0
	global_load_lds_dwordx4 v[146:147], off
	v_add_u32_e32 v146, 0xe000, v148
	s_nop 0
	v_readfirstlane_b32 s20, v146
	s_mov_b32 m0, s20
	s_nop 0
	global_load_lds_dwordx4 v[144:145], off
	s_branch .LBB0_175

.LBB0_187:
	v_add_u32_e32 v218, s1, v201
	v_add3_u32 v214, v218, v160, v161
	v_add3_u32 v230, v218, v198, v161
	ds_read_b128 v[154:157], v214 offset:32768
	ds_read_b128 v[214:217], v214 offset:36864
	ds_read_b128 v[218:221], v230
	ds_read_b128 v[222:225], v230 offset:4096
	ds_read_b128 v[226:229], v230 offset:8192
	ds_read_b128 v[230:233], v230 offset:12288
	s_setprio 1
	s_waitcnt lgkmcnt(3)
	v_mfma_f32_32x32x16_bf16 v[112:127], v[154:157], v[218:221], v[112:127]
	s_waitcnt lgkmcnt(2)
	v_mfma_f32_32x32x16_bf16 v[96:111], v[154:157], v[222:225], v[96:111]
	s_waitcnt lgkmcnt(1)
	v_mfma_f32_32x32x16_bf16 v[48:63], v[154:157], v[226:229], v[48:63]
	s_waitcnt lgkmcnt(0)
	v_mfma_f32_32x32x16_bf16 v[32:47], v[154:157], v[230:233], v[32:47]
	v_mfma_f32_32x32x16_bf16 v[80:95], v[214:217], v[218:221], v[80:95]
	v_mfma_f32_32x32x16_bf16 v[64:79], v[214:217], v[222:225], v[64:79]
	v_mfma_f32_32x32x16_bf16 v[16:31], v[214:217], v[226:229], v[16:31]
	v_mfma_f32_32x32x16_bf16 v[0:15], v[214:217], v[230:233], v[0:15]
	s_setprio 0
	s_waitcnt vmcnt(0)
	s_add_u32 s34, s34, 0x80
	s_addc_u32 s35, s35, 0
	s_cmpk_eq_i32 s34, 0x800
	s_waitcnt vmcnt(0)
	s_barrier
	s_cbranch_scc1 .LBB0_194

.LBB0_190:
	v_lshl_add_u64 v[154:155], v[150:151], 0, s[34:35]
	v_add_u32_e32 v215, s1, v199
	v_add3_u32 v220, v215, v160, v161
	v_add3_u32 v215, v215, v198, v161
	ds_read_b128 v[216:219], v220 offset:32768
	ds_read_b128 v[220:223], v220 offset:36864
	ds_read_b128 v[224:227], v215
	ds_read_b128 v[228:231], v215 offset:4096
	ds_read_b128 v[232:235], v215 offset:8192
	ds_read_b128 v[236:239], v215 offset:12288
	s_setprio 1
	s_waitcnt lgkmcnt(3)
	v_mfma_f32_32x32x16_bf16 v[112:127], v[216:219], v[224:227], v[112:127]
	s_waitcnt lgkmcnt(2)
	v_mfma_f32_32x32x16_bf16 v[96:111], v[216:219], v[228:231], v[96:111]
	s_waitcnt lgkmcnt(1)
	v_mfma_f32_32x32x16_bf16 v[48:63], v[216:219], v[232:235], v[48:63]
	s_waitcnt lgkmcnt(0)
	v_mfma_f32_32x32x16_bf16 v[32:47], v[216:219], v[236:239], v[32:47]
	v_mfma_f32_32x32x16_bf16 v[80:95], v[220:223], v[224:227], v[80:95]
	v_mfma_f32_32x32x16_bf16 v[64:79], v[220:223], v[228:231], v[64:79]
	v_mfma_f32_32x32x16_bf16 v[16:31], v[220:223], v[232:235], v[16:31]
	v_mfma_f32_32x32x16_bf16 v[0:15], v[220:223], v[236:239], v[0:15]
	s_setprio 0
	v_cndmask_b32_e64 v215, 0, 1, s[48:49]
	v_cmp_ne_u32_e64 s[38:39], 1, v215
	s_andn2_b64 vcc, exec, s[48:49]
	s_cbranch_vccnz .LBB0_192
	s_mov_b64 s[20:21], 0x2ffcc080
	v_lshl_add_u64 v[156:157], v[156:157], 0, s[20:21]
	s_mov_b64 s[20:21], 0x1800080
	v_lshl_add_u64 v[216:217], v[154:155], 0, s[20:21]
	s_mov_b64 s[20:21], 0x1820080
	v_add_u32_e32 v215, 0x6000, v214
	v_lshl_add_u64 v[218:219], v[154:155], 0, s[20:21]
	v_readfirstlane_b32 s20, v215
	s_mov_b32 m0, s20
	s_nop 0
	global_load_lds_dwordx4 v[156:157], off
	v_add_u32_e32 v156, 0x8000, v214
	s_nop 0
	v_readfirstlane_b32 s20, v156
	v_add_u32_e32 v156, 0xa000, v214
	s_mov_b32 m0, s20
	v_readfirstlane_b32 s20, v156
	global_load_lds_dwordx4 v[216:217], off
	s_mov_b32 m0, s20
	s_nop 0
	global_load_lds_dwordx4 v[218:219], off
.LBB0_192:
	v_add_u32_e32 v156, s1, v200
	v_add3_u32 v157, v156, v160, v161
	v_add3_u32 v156, v156, v198, v161
	ds_read_b128 v[216:219], v157 offset:32768
	ds_read_b128 v[220:223], v157 offset:36864
	ds_read_b128 v[224:227], v156
	ds_read_b128 v[228:231], v156 offset:4096
	ds_read_b128 v[232:235], v156 offset:8192
	ds_read_b128 v[236:239], v156 offset:12288
	s_setprio 1
	s_waitcnt lgkmcnt(3)
	v_mfma_f32_32x32x16_bf16 v[112:127], v[216:219], v[224:227], v[112:127]
	s_waitcnt lgkmcnt(2)
	v_mfma_f32_32x32x16_bf16 v[96:111], v[216:219], v[228:231], v[96:111]
	s_waitcnt lgkmcnt(1)
	v_mfma_f32_32x32x16_bf16 v[48:63], v[216:219], v[232:235], v[48:63]
	s_waitcnt lgkmcnt(0)
	v_mfma_f32_32x32x16_bf16 v[32:47], v[216:219], v[236:239], v[32:47]
	v_mfma_f32_32x32x16_bf16 v[80:95], v[220:223], v[224:227], v[80:95]
	v_mfma_f32_32x32x16_bf16 v[64:79], v[220:223], v[228:231], v[64:79]
	v_mfma_f32_32x32x16_bf16 v[16:31], v[220:223], v[232:235], v[16:31]
	v_mfma_f32_32x32x16_bf16 v[0:15], v[220:223], v[236:239], v[0:15]
	s_setprio 0
	s_and_b64 vcc, exec, s[38:39]
	s_cbranch_vccnz .LBB0_187
	s_mov_b64 s[20:21], 0x1840080
	v_lshl_add_u64 v[156:157], v[154:155], 0, s[20:21]
	s_mov_b64 s[20:21], 0x1860080
	v_add_u32_e32 v215, 0xc000, v214
	v_lshl_add_u64 v[154:155], v[154:155], 0, s[20:21]
	v_readfirstlane_b32 s20, v215
	s_mov_b32 m0, s20
	s_nop 0
	global_load_lds_dwordx4 v[156:157], off
	v_add_u32_e32 v156, 0xe000, v214
	s_nop 0
	v_readfirstlane_b32 s20, v156
	s_mov_b32 m0, s20
	s_nop 0
	global_load_lds_dwordx4 v[154:155], off
	s_branch .LBB0_187

.LBB0_331:
	v_add_u32_e32 v214, s1, v161
	v_add3_u32 v210, v214, v156, v157
	v_add3_u32 v226, v214, v158, v157
	ds_read_b128 v[150:153], v210 offset:32768
	ds_read_b128 v[210:213], v210 offset:36864
	ds_read_b128 v[214:217], v226
	ds_read_b128 v[218:221], v226 offset:4096
	ds_read_b128 v[222:225], v226 offset:8192
	ds_read_b128 v[226:229], v226 offset:12288
	s_setprio 1
	s_waitcnt lgkmcnt(3)
	v_mfma_f32_32x32x16_bf16 v[112:127], v[150:153], v[214:217], v[112:127]
	s_waitcnt lgkmcnt(2)
	v_mfma_f32_32x32x16_bf16 v[96:111], v[150:153], v[218:221], v[96:111]
	s_waitcnt lgkmcnt(1)
	v_mfma_f32_32x32x16_bf16 v[48:63], v[150:153], v[222:225], v[48:63]
	s_waitcnt lgkmcnt(0)
	v_mfma_f32_32x32x16_bf16 v[32:47], v[150:153], v[226:229], v[32:47]
	v_mfma_f32_32x32x16_bf16 v[80:95], v[210:213], v[214:217], v[80:95]
	v_mfma_f32_32x32x16_bf16 v[64:79], v[210:213], v[218:221], v[64:79]
	v_mfma_f32_32x32x16_bf16 v[16:31], v[210:213], v[222:225], v[16:31]
	v_mfma_f32_32x32x16_bf16 v[0:15], v[210:213], v[226:229], v[0:15]
	s_setprio 0
	s_waitcnt vmcnt(0)
	s_add_u32 s50, s50, 0x80
	s_addc_u32 s51, s51, 0
	s_cmpk_eq_i32 s50, 0x800
	s_waitcnt vmcnt(0)
	s_barrier
	s_cbranch_scc1 .LBB0_338

.LBB0_334:
	v_lshl_add_u64 v[150:151], v[146:147], 0, s[50:51]
	v_add_u32_e32 v211, s1, v159
	v_add3_u32 v216, v211, v156, v157
	v_add3_u32 v211, v211, v158, v157
	ds_read_b128 v[212:215], v216 offset:32768
	ds_read_b128 v[216:219], v216 offset:36864
	ds_read_b128 v[220:223], v211
	ds_read_b128 v[224:227], v211 offset:4096
	ds_read_b128 v[228:231], v211 offset:8192
	ds_read_b128 v[232:235], v211 offset:12288
	s_setprio 1
	s_waitcnt lgkmcnt(3)
	v_mfma_f32_32x32x16_bf16 v[112:127], v[212:215], v[220:223], v[112:127]
	s_waitcnt lgkmcnt(2)
	v_mfma_f32_32x32x16_bf16 v[96:111], v[212:215], v[224:227], v[96:111]
	s_waitcnt lgkmcnt(1)
	v_mfma_f32_32x32x16_bf16 v[48:63], v[212:215], v[228:231], v[48:63]
	s_waitcnt lgkmcnt(0)
	v_mfma_f32_32x32x16_bf16 v[32:47], v[212:215], v[232:235], v[32:47]
	v_mfma_f32_32x32x16_bf16 v[80:95], v[216:219], v[220:223], v[80:95]
	v_mfma_f32_32x32x16_bf16 v[64:79], v[216:219], v[224:227], v[64:79]
	v_mfma_f32_32x32x16_bf16 v[16:31], v[216:219], v[228:231], v[16:31]
	v_mfma_f32_32x32x16_bf16 v[0:15], v[216:219], v[232:235], v[0:15]
	s_setprio 0
	v_cndmask_b32_e64 v211, 0, 1, s[52:53]
	v_cmp_ne_u32_e64 s[38:39], 1, v211
	s_andn2_b64 vcc, exec, s[52:53]
	s_cbranch_vccnz .LBB0_336
	s_mov_b64 s[20:21], 0x35fcc080
	v_lshl_add_u64 v[152:153], v[152:153], 0, s[20:21]
	s_mov_b64 s[20:21], 0x1a00080
	v_lshl_add_u64 v[212:213], v[150:151], 0, s[20:21]
	s_mov_b64 s[20:21], 0x1a20080
	v_add_u32_e32 v211, 0x6000, v210
	v_lshl_add_u64 v[214:215], v[150:151], 0, s[20:21]
	v_readfirstlane_b32 s20, v211
	s_mov_b32 m0, s20
	s_nop 0
	global_load_lds_dwordx4 v[152:153], off
	v_add_u32_e32 v152, 0x8000, v210
	s_nop 0
	v_readfirstlane_b32 s20, v152
	v_add_u32_e32 v152, 0xa000, v210
	s_mov_b32 m0, s20
	v_readfirstlane_b32 s20, v152
	global_load_lds_dwordx4 v[212:213], off
	s_mov_b32 m0, s20
	s_nop 0
	global_load_lds_dwordx4 v[214:215], off
.LBB0_336:
	v_add_u32_e32 v152, s1, v160
	v_add3_u32 v153, v152, v156, v157
	v_add3_u32 v152, v152, v158, v157
	ds_read_b128 v[212:215], v153 offset:32768
	ds_read_b128 v[216:219], v153 offset:36864
	ds_read_b128 v[220:223], v152
	ds_read_b128 v[224:227], v152 offset:4096
	ds_read_b128 v[228:231], v152 offset:8192
	ds_read_b128 v[232:235], v152 offset:12288
	s_setprio 1
	s_waitcnt lgkmcnt(3)
	v_mfma_f32_32x32x16_bf16 v[112:127], v[212:215], v[220:223], v[112:127]
	s_waitcnt lgkmcnt(2)
	v_mfma_f32_32x32x16_bf16 v[96:111], v[212:215], v[224:227], v[96:111]
	s_waitcnt lgkmcnt(1)
	v_mfma_f32_32x32x16_bf16 v[48:63], v[212:215], v[228:231], v[48:63]
	s_waitcnt lgkmcnt(0)
	v_mfma_f32_32x32x16_bf16 v[32:47], v[212:215], v[232:235], v[32:47]
	v_mfma_f32_32x32x16_bf16 v[80:95], v[216:219], v[220:223], v[80:95]
	v_mfma_f32_32x32x16_bf16 v[64:79], v[216:219], v[224:227], v[64:79]
	v_mfma_f32_32x32x16_bf16 v[16:31], v[216:219], v[228:231], v[16:31]
	v_mfma_f32_32x32x16_bf16 v[0:15], v[216:219], v[232:235], v[0:15]
	s_setprio 0
	s_and_b64 vcc, exec, s[38:39]
	s_cbranch_vccnz .LBB0_331
	s_mov_b64 s[20:21], 0x1a40080
	v_lshl_add_u64 v[152:153], v[150:151], 0, s[20:21]
	s_mov_b64 s[20:21], 0x1a60080
	v_add_u32_e32 v211, 0xc000, v210
	v_lshl_add_u64 v[150:151], v[150:151], 0, s[20:21]
	v_readfirstlane_b32 s20, v211
	s_mov_b32 m0, s20
	s_nop 0
	global_load_lds_dwordx4 v[152:153], off
	v_add_u32_e32 v152, 0xe000, v210
	s_nop 0
	v_readfirstlane_b32 s20, v152
	s_mov_b32 m0, s20
	s_nop 0
	global_load_lds_dwordx4 v[150:151], off
	s_branch .LBB0_331

.LBB0_373:
	v_add_u32_e32 v222, s1, v199
	v_add3_u32 v218, v222, v158, v159
	v_add3_u32 v234, v222, v160, v159
	ds_read_b128 v[150:153], v218 offset:32768
	ds_read_b128 v[218:221], v218 offset:36864
	ds_read_b128 v[222:225], v234
	ds_read_b128 v[226:229], v234 offset:4096
	ds_read_b128 v[230:233], v234 offset:8192
	ds_read_b128 v[234:237], v234 offset:12288
	s_setprio 1
	s_waitcnt lgkmcnt(3)
	v_mfma_f32_32x32x16_bf16 v[112:127], v[150:153], v[222:225], v[112:127]
	s_waitcnt lgkmcnt(2)
	v_mfma_f32_32x32x16_bf16 v[96:111], v[150:153], v[226:229], v[96:111]
	s_waitcnt lgkmcnt(1)
	v_mfma_f32_32x32x16_bf16 v[48:63], v[150:153], v[230:233], v[48:63]
	s_waitcnt lgkmcnt(0)
	v_mfma_f32_32x32x16_bf16 v[32:47], v[150:153], v[234:237], v[32:47]
	v_mfma_f32_32x32x16_bf16 v[80:95], v[218:221], v[222:225], v[80:95]
	v_mfma_f32_32x32x16_bf16 v[64:79], v[218:221], v[226:229], v[64:79]
	v_mfma_f32_32x32x16_bf16 v[16:31], v[218:221], v[230:233], v[16:31]
	v_mfma_f32_32x32x16_bf16 v[0:15], v[218:221], v[234:237], v[0:15]
	s_setprio 0
	s_waitcnt vmcnt(0)
	s_add_u32 s40, s40, 0x80
	s_addc_u32 s41, s41, 0
	s_cmpk_eq_i32 s40, 0x800
	s_waitcnt vmcnt(0)
	s_barrier
	s_cbranch_scc1 .LBB0_380

.LBB0_376:
	v_lshl_add_u64 v[150:151], v[128:129], 0, s[40:41]
	v_add_u32_e32 v219, s1, v161
	v_add3_u32 v224, v219, v158, v159
	v_add3_u32 v219, v219, v160, v159
	ds_read_b128 v[220:223], v224 offset:32768
	ds_read_b128 v[224:227], v224 offset:36864
	ds_read_b128 v[228:231], v219
	ds_read_b128 v[232:235], v219 offset:4096
	ds_read_b128 v[236:239], v219 offset:8192
	ds_read_b128 v[240:243], v219 offset:12288
	s_setprio 1
	s_waitcnt lgkmcnt(3)
	v_mfma_f32_32x32x16_bf16 v[112:127], v[220:223], v[228:231], v[112:127]
	s_waitcnt lgkmcnt(2)
	v_mfma_f32_32x32x16_bf16 v[96:111], v[220:223], v[232:235], v[96:111]
	s_waitcnt lgkmcnt(1)
	v_mfma_f32_32x32x16_bf16 v[48:63], v[220:223], v[236:239], v[48:63]
	s_waitcnt lgkmcnt(0)
	v_mfma_f32_32x32x16_bf16 v[32:47], v[220:223], v[240:243], v[32:47]
	v_mfma_f32_32x32x16_bf16 v[80:95], v[224:227], v[228:231], v[80:95]
	v_mfma_f32_32x32x16_bf16 v[64:79], v[224:227], v[232:235], v[64:79]
	v_mfma_f32_32x32x16_bf16 v[16:31], v[224:227], v[236:239], v[16:31]
	v_mfma_f32_32x32x16_bf16 v[0:15], v[224:227], v[240:243], v[0:15]
	s_setprio 0
	v_cndmask_b32_e64 v219, 0, 1, s[42:43]
	v_cmp_ne_u32_e64 s[38:39], 1, v219
	s_andn2_b64 vcc, exec, s[42:43]
	s_cbranch_vccnz .LBB0_378
	s_mov_b64 s[20:21], 0x67cc080
	v_lshl_add_u64 v[152:153], v[152:153], 0, s[20:21]
	s_mov_b64 s[20:21], 0x80
	v_lshl_add_u64 v[220:221], v[150:151], 0, s[20:21]
	s_mov_b64 s[20:21], 0x20080
	v_add_u32_e32 v219, 0x6000, v218
	v_lshl_add_u64 v[222:223], v[150:151], 0, s[20:21]
	v_readfirstlane_b32 s20, v219
	s_mov_b32 m0, s20
	s_nop 0
	global_load_lds_dwordx4 v[152:153], off
	v_add_u32_e32 v152, 0x8000, v218
	s_nop 0
	v_readfirstlane_b32 s20, v152
	v_add_u32_e32 v152, 0xa000, v218
	s_mov_b32 m0, s20
	v_readfirstlane_b32 s20, v152
	global_load_lds_dwordx4 v[220:221], off
	s_mov_b32 m0, s20
	s_nop 0
	global_load_lds_dwordx4 v[222:223], off
.LBB0_378:
	v_add_u32_e32 v152, s1, v198
	v_add3_u32 v153, v152, v158, v159
	v_add3_u32 v152, v152, v160, v159
	ds_read_b128 v[220:223], v153 offset:32768
	ds_read_b128 v[224:227], v153 offset:36864
	ds_read_b128 v[228:231], v152
	ds_read_b128 v[232:235], v152 offset:4096
	ds_read_b128 v[236:239], v152 offset:8192
	ds_read_b128 v[240:243], v152 offset:12288
	s_setprio 1
	s_waitcnt lgkmcnt(3)
	v_mfma_f32_32x32x16_bf16 v[112:127], v[220:223], v[228:231], v[112:127]
	s_waitcnt lgkmcnt(2)
	v_mfma_f32_32x32x16_bf16 v[96:111], v[220:223], v[232:235], v[96:111]
	s_waitcnt lgkmcnt(1)
	v_mfma_f32_32x32x16_bf16 v[48:63], v[220:223], v[236:239], v[48:63]
	s_waitcnt lgkmcnt(0)
	v_mfma_f32_32x32x16_bf16 v[32:47], v[220:223], v[240:243], v[32:47]
	v_mfma_f32_32x32x16_bf16 v[80:95], v[224:227], v[228:231], v[80:95]
	v_mfma_f32_32x32x16_bf16 v[64:79], v[224:227], v[232:235], v[64:79]
	v_mfma_f32_32x32x16_bf16 v[16:31], v[224:227], v[236:239], v[16:31]
	v_mfma_f32_32x32x16_bf16 v[0:15], v[224:227], v[240:243], v[0:15]
	s_setprio 0
	s_and_b64 vcc, exec, s[38:39]
	s_cbranch_vccnz .LBB0_373
	s_mov_b64 s[20:21], 0x40080
	v_lshl_add_u64 v[152:153], v[150:151], 0, s[20:21]
	s_mov_b64 s[20:21], 0x60080
	v_add_u32_e32 v219, 0xc000, v218
	v_lshl_add_u64 v[150:151], v[150:151], 0, s[20:21]
	v_readfirstlane_b32 s20, v219
	s_mov_b32 m0, s20
	s_nop 0
	global_load_lds_dwordx4 v[152:153], off
	v_add_u32_e32 v152, 0xe000, v218
	s_nop 0
	v_readfirstlane_b32 s20, v152
	s_mov_b32 m0, s20
	s_nop 0
	global_load_lds_dwordx4 v[150:151], off
	s_branch .LBB0_373
